# EpiX GEMMs (out-proj, ffn-down): touch the x tile's cache lines with 4 dword loads per thread at tile start so the read-modify-write epilogue hits cache
# baseline (speedup 1.0000x reference)
; #define SSTOREG(buf_) do { char* b_ = (buf_) + lo; \
;       *(uint4*)(b_) = ra0; *(uint4*)(b_ + 64 * GSTR) = ra1; *(uint4*)(b_ + 128 * GSTR) = ra2; *(uint4*)(b_ + 192 * GSTR) = ra3; \
;       *(uint4*)(b_ + 256 * GSTR) = rw0; *(uint4*)(b_ + 320 * GSTR) = rw1; \
;       if (WM == 2) { *(uint4*)(b_ + 384 * GSTR) = rw2; *(uint4*)(b_ + 448 * GSTR) = rw3; } } while (0)
; #define SSTOREG(buf_) do { char* b_ = (buf_) + lo; \
;       *(uint4*)(b_) = ra0; *(uint4*)(b_ + 64 * GSTR) = ra1; *(uint4*)(b_ + 128 * GSTR) = ra2; *(uint4*)(b_ + 192 * GSTR) = ra3; \
;       *(uint4*)(b_ + 256 * GSTR) = rw0; *(uint4*)(b_ + 320 * GSTR) = rw1; \
;       if (WM == 2) { *(uint4*)(b_ + 384 * GSTR) = rw2; *(uint4*)(b_ + 448 * GSTR) = rw3; } } while (0)
;     ...
;   for (int u = slot; u < nunits; u += nslots) {
;     const bool part = u >= full;
;     const int q = part ? full + (u - full) / NSP : u, ks = part ? (u - full) % NSP : 0;
;     const int mtl = q / ntiles, nt = q - mtl * ntiles, mt = mtl * 8 + xcd;
;     if (skipctx && (mt % PT) == 0) continue;
;     const int kt0 = part ? (ks * nk) / NSP : 0, kt1 = part ? ((ks + 1) * nk) / NSP : nk;
;     const bf16_t* Ag = A + (size_t)mt * 256 * K;
;     const bf16_t* Wg = W + (size_t)nt * BN * K;
;     f32x16 acc[WM][4];
; #pragma unroll
;     for (int mi = 0; mi < WM; ++mi)
; #pragma unroll
;       for (int nb = 0; nb < 4; ++nb)
; #pragma unroll
;         for (int i = 0; i < 16; ++i) acc[mi][nb][i] = 0.f;
;     uint4 ra0, ra1, ra2, ra3, rw0, rw1, rw2, rw3;
;     rw2 = make_uint4(0, 0, 0, 0); rw3 = rw2;
;     const int grow = tid >> 3, gcol = (tid & 7) * 8;
;     const bf16_t* ap = Ag + (size_t)grow * K + gcol;
;     const bf16_t* wp = Wg + (size_t)grow * K + gcol;
;     const int lo = grow * GSTR + (tid & 7) * 16;
;     ...
;     GLOADG(kt0); SSTOREG(smem);
;     if (WM == 2) GLOADG(kt0 + 1 < kt1 ? kt0 + 1 : kt0);
;   DI void operator()(f32x16 (&acc)[4], int tok0, int nt, int lane, bool part = false) const {
;     ...
;     const int b = tok0 / PL, pp0 = tok0 - b * PL;
;     const float* g = gate + (size_t)(pp0 < CTXL ? 4 : b) * 6144;
;     float* xb = pp0 < CTXL ? (float*)(p->ws + OFF_CTXX) + (size_t)(b * CTXL + pp0) * DM : p->out + (size_t)(b * SEQ + pp0 - CTXL) * DM;
.LBB0_21:
	s_cmp_ge_i32 s45, s46
	s_cselect_b64 s[0:1], -1, 0
	s_sub_i32 s24, s45, s46
	s_lshr_b32 s25, s24, 3
	s_add_i32 s25, s25, s46
	s_cmp_lt_i32 s45, s46
	s_cselect_b64 s[28:29], -1, 0
	s_and_b64 s[30:31], s[28:29], exec
	s_cselect_b32 s25, s45, s25
	s_ashr_i32 s27, s25, 31
	s_lshr_b32 s27, s27, 30
	s_add_i32 s27, s25, s27
	s_ashr_i32 s27, s27, 2
	s_lshl_b32 s30, s27, 3
	s_or_b32 s30, s30, s3
	s_mul_hi_i32 s31, s30, 0x3e0f83e1
	s_lshr_b32 s36, s31, 31
	s_ashr_i32 s31, s31, 3
	s_add_i32 s31, s31, s36
	s_mul_i32 s31, s31, 33
	s_sub_i32 s31, s30, s31
	s_cmp_eq_u32 s31, 0
	s_cselect_b64 s[36:37], -1, 0
	s_and_b64 s[36:37], s[40:41], s[36:37]
	s_and_b64 vcc, exec, s[36:37]
	s_cbranch_vccnz .LBB0_20
	s_and_b32 s24, s24, 7
	s_lshl_b32 s27, s27, 2
	s_mul_i32 s24, s24, 44
	s_sub_i32 s31, s25, s27
	s_lshr_b32 s27, s24, 3
	s_add_i32 s24, s24, 44
	s_lshr_b32 s36, s24, 3
	v_mov_b32_e32 v0, 0x160000
	s_and_b64 s[24:25], s[28:29], exec
	v_mad_i64_i32 v[170:171], s[24:25], s30, v0, v[162:163]
	v_mad_i64_i32 v[172:173], s[24:25], s31, v0, v[164:165]
	s_cselect_b32 s28, 0, s27
	s_mov_b64 s[24:25], 0x58000
	s_cselect_b32 s29, 44, s36
	s_lshl_b32 s96, s28, 7
	v_lshl_add_u64 v[174:175], v[170:171], 0, s[24:25]
	s_waitcnt vmcnt(6)
	v_lshl_add_u64 v[180:181], v[172:173], 0, s[24:25]
	s_add_i32 s24, s28, 1
	s_mov_b64 s[36:37], 0xb0000
	s_mov_b64 s[38:39], 0x108000
	s_cmp_lt_u32 s24, s29
	v_lshl_add_u64 v[176:177], v[170:171], 0, s[36:37]
	s_waitcnt vmcnt(4)
	v_lshl_add_u64 v[178:179], v[170:171], 0, s[38:39]
	v_lshl_add_u64 v[182:183], v[172:173], 0, s[36:37]
	v_lshl_add_u64 v[184:185], v[172:173], 0, s[38:39]
	s_cselect_b32 s24, s24, s28
	v_lshl_add_u64 v[0:1], v[170:171], 0, s[96:97]
	v_lshl_add_u64 v[4:5], v[174:175], 0, s[96:97]
	v_lshl_add_u64 v[8:9], v[176:177], 0, s[96:97]
	v_lshl_add_u64 v[12:13], v[178:179], 0, s[96:97]
	v_lshl_add_u64 v[16:17], v[172:173], 0, s[96:97]
	v_lshl_add_u64 v[20:21], v[180:181], 0, s[96:97]
	v_lshl_add_u64 v[24:25], v[182:183], 0, s[96:97]
	v_lshl_add_u64 v[28:29], v[184:185], 0, s[96:97]
	s_lshl_b32 s96, s24, 7
	v_lshl_add_u64 v[32:33], v[170:171], 0, s[96:97]
	global_load_dwordx4 v[0:3], v[0:1], off
	s_nop 0
	global_load_dwordx4 v[4:7], v[4:5], off
	s_nop 0
	global_load_dwordx4 v[8:11], v[8:9], off
	s_nop 0
	global_load_dwordx4 v[12:15], v[12:13], off
	s_nop 0
	global_load_dwordx4 v[16:19], v[16:17], off
	s_nop 0
	global_load_dwordx4 v[20:23], v[20:21], off
	s_nop 0
	global_load_dwordx4 v[24:27], v[24:25], off
	s_nop 0
	global_load_dwordx4 v[28:31], v[28:29], off
	v_lshl_add_u64 v[34:35], v[174:175], 0, s[96:97]
	v_lshl_add_u64 v[36:37], v[176:177], 0, s[96:97]
	v_lshl_add_u64 v[38:39], v[178:179], 0, s[96:97]
	v_lshl_add_u64 v[40:41], v[172:173], 0, s[96:97]
	v_lshl_add_u64 v[42:43], v[180:181], 0, s[96:97]
	v_lshl_add_u64 v[44:45], v[182:183], 0, s[96:97]
	v_lshl_add_u64 v[46:47], v[184:185], 0, s[96:97]
	global_load_dwordx4 v[158:161], v[32:33], off
	global_load_dwordx4 v[154:157], v[34:35], off
	global_load_dwordx4 v[150:153], v[36:37], off
	global_load_dwordx4 v[146:149], v[38:39], off
	global_load_dwordx4 v[142:145], v[40:41], off
	global_load_dwordx4 v[136:139], v[42:43], off
	global_load_dwordx4 v[132:135], v[44:45], off
	global_load_dwordx4 v[128:131], v[46:47], off
	s_mul_i32 s32, s30, 0x7c2
	s_lshr_b32 s32, s32, 16
	s_mul_i32 s98, s32, 33
	s_sub_u32 s98, s30, s98
	s_cmp_eq_u32 s98, 0
	s_cbranch_scc1 .Lpf1_ctx
	s_lshl_b32 s99, s98, 8
	s_lshl_b32 s32, s32, 13
	s_add_u32 s32, s32, s99
	s_addk_i32 s32, 0xff00
	v_readlane_b32 s98, v254, 59
	v_readlane_b32 s99, v254, 60
	s_branch .Lpf1_join
.Lpf1_ctx:
	s_lshl_b32 s32, s32, 8
	v_readlane_b32 s98, v252, 8
	v_readlane_b32 s99, v252, 9
.Lpf1_join:
	s_lshl_b32 s32, s32, 12
	s_add_u32 s98, s98, s32
	s_addc_u32 s99, s99, 0
	v_lshrrev_b32_e32 v250, 3, v167
	v_and_b32_e32 v251, 7, v167
	v_lshlrev_b32_e32 v250, 12, v250
	v_lshl_or_b32 v250, v251, 7, v250
	v_lshl_add_u32 v250, s31, 10, v250
	global_load_dword v251, v250, s[98:99]
	v_add_u32_e32 v250, 0x40000, v250
	global_load_dword v251, v250, s[98:99]
	v_add_u32_e32 v250, 0x40000, v250
	global_load_dword v251, v250, s[98:99]
	v_add_u32_e32 v250, 0x40000, v250
	global_load_dword v251, v250, s[98:99]
	v_mov_b32_e32 v127, 0
	v_mov_b32_e32 v126, v127
	v_mov_b32_e32 v125, v127
	v_mov_b32_e32 v124, v127
	v_mov_b32_e32 v123, v127
	v_mov_b32_e32 v122, v127
	v_mov_b32_e32 v121, v127
	v_mov_b32_e32 v120, v127
	v_mov_b32_e32 v119, v127
	v_mov_b32_e32 v118, v127
	v_mov_b32_e32 v117, v127
	v_mov_b32_e32 v116, v127
	v_mov_b32_e32 v115, v127
	v_mov_b32_e32 v114, v127
	v_mov_b32_e32 v113, v127
	v_mov_b32_e32 v112, v127
	v_mov_b32_e32 v111, v127
	v_mov_b32_e32 v110, v127
	v_mov_b32_e32 v109, v127
	v_mov_b32_e32 v108, v127
	s_cmp_ge_u32 s28, s29
	v_mov_b32_e32 v107, v127
	v_mov_b32_e32 v106, v127
	s_waitcnt vmcnt(23)
	v_mov_b32_e32 v105, v127
	s_waitcnt vmcnt(22)
	v_mov_b32_e32 v104, v127
	s_waitcnt vmcnt(21)
	v_mov_b32_e32 v103, v127
	s_waitcnt vmcnt(20)
	v_mov_b32_e32 v102, v127
	v_mov_b32_e32 v101, v127
	v_mov_b32_e32 v100, v127
	v_mov_b32_e32 v99, v127
	v_mov_b32_e32 v98, v127
	v_mov_b32_e32 v97, v127
	v_mov_b32_e32 v96, v127
	v_mov_b32_e32 v95, v127
	v_mov_b32_e32 v94, v127
	v_mov_b32_e32 v93, v127
	v_mov_b32_e32 v92, v127
	v_mov_b32_e32 v91, v127
	s_waitcnt vmcnt(19)
	ds_write_b128 v188, v[0:3]
	s_waitcnt vmcnt(18)
	ds_write_b128 v188, v[4:7] offset:9216
	s_waitcnt vmcnt(17)
	ds_write_b128 v188, v[8:11] offset:18432
	s_waitcnt vmcnt(16)
	ds_write_b128 v188, v[12:15] offset:27648
	s_waitcnt vmcnt(15)
; #define SSTOREG(buf_) do { char* b_ = (buf_) + lo; \
;       *(uint4*)(b_) = ra0; *(uint4*)(b_ + 64 * GSTR) = ra1; *(uint4*)(b_ + 128 * GSTR) = ra2; *(uint4*)(b_ + 192 * GSTR) = ra3; \
;       *(uint4*)(b_ + 256 * GSTR) = rw0; *(uint4*)(b_ + 320 * GSTR) = rw1; \
;       if (WM == 2) { *(uint4*)(b_ + 384 * GSTR) = rw2; *(uint4*)(b_ + 448 * GSTR) = rw3; } } while (0)
; #define SSTOREG(buf_) do { char* b_ = (buf_) + lo; \
;       *(uint4*)(b_) = ra0; *(uint4*)(b_ + 64 * GSTR) = ra1; *(uint4*)(b_ + 128 * GSTR) = ra2; *(uint4*)(b_ + 192 * GSTR) = ra3; \
;       *(uint4*)(b_ + 256 * GSTR) = rw0; *(uint4*)(b_ + 320 * GSTR) = rw1; \
;       if (WM == 2) { *(uint4*)(b_ + 384 * GSTR) = rw2; *(uint4*)(b_ + 448 * GSTR) = rw3; } } while (0)
;     ...
;     f32x16 acc[WM][4];
; #pragma unroll
;     for (int mi = 0; mi < WM; ++mi)
; #pragma unroll
;       for (int nb = 0; nb < 4; ++nb)
; #pragma unroll
;         for (int i = 0; i < 16; ++i) acc[mi][nb][i] = 0.f;
;     uint4 ra0, ra1, ra2, ra3, rw0, rw1, rw2, rw3;
;     rw2 = make_uint4(0, 0, 0, 0); rw3 = rw2;
;     const int grow = tid >> 3, gcol = (tid & 7) * 8;
;     const bf16_t* ap = Ag + (size_t)grow * K + gcol;
;     const bf16_t* wp = Wg + (size_t)grow * K + gcol;
;     const int lo = grow * GSTR + (tid & 7) * 16;
;     ...
;     GLOADG(kt0); SSTOREG(smem);
;     if (WM == 2) GLOADG(kt0 + 1 < kt1 ? kt0 + 1 : kt0);
;     __syncthreads();
	ds_write_b128 v188, v[16:19] offset:36864
	s_waitcnt vmcnt(14)
	ds_write_b128 v188, v[20:23] offset:46080
	s_waitcnt vmcnt(13)
	ds_write_b128 v188, v[24:27] offset:55296
	s_waitcnt vmcnt(12)
	ds_write_b128 v188, v[28:31] offset:64512
	v_mov_b32_e32 v90, v127
	v_mov_b32_e32 v89, v127
	v_mov_b32_e32 v88, v127
	v_mov_b32_e32 v87, v127
	v_mov_b32_e32 v86, v127
	v_mov_b32_e32 v85, v127
	v_mov_b32_e32 v84, v127
	v_mov_b32_e32 v83, v127
	v_mov_b32_e32 v82, v127
	v_mov_b32_e32 v81, v127
	v_mov_b32_e32 v80, v127
	v_mov_b32_e32 v79, v127
	v_mov_b32_e32 v78, v127
	v_mov_b32_e32 v77, v127
	v_mov_b32_e32 v76, v127
	v_mov_b32_e32 v75, v127
	v_mov_b32_e32 v74, v127
	v_mov_b32_e32 v73, v127
	v_mov_b32_e32 v72, v127
	v_mov_b32_e32 v71, v127
	v_mov_b32_e32 v70, v127
	v_mov_b32_e32 v69, v127
	v_mov_b32_e32 v68, v127
	v_mov_b32_e32 v67, v127
	v_mov_b32_e32 v66, v127
	v_mov_b32_e32 v65, v127
	v_mov_b32_e32 v64, v127
	v_mov_b32_e32 v63, v127
	v_mov_b32_e32 v62, v127
	v_mov_b32_e32 v61, v127
	v_mov_b32_e32 v60, v127
	v_mov_b32_e32 v59, v127
	v_mov_b32_e32 v58, v127
	v_mov_b32_e32 v57, v127
	v_mov_b32_e32 v56, v127
	v_mov_b32_e32 v55, v127
	v_mov_b32_e32 v54, v127
	v_mov_b32_e32 v53, v127
	v_mov_b32_e32 v52, v127
	v_mov_b32_e32 v51, v127
	v_mov_b32_e32 v50, v127
	v_mov_b32_e32 v49, v127
	v_mov_b32_e32 v48, v127
	v_mov_b32_e32 v47, v127
	v_mov_b32_e32 v46, v127
	v_mov_b32_e32 v45, v127
	v_mov_b32_e32 v44, v127
	v_mov_b32_e32 v43, v127
	v_mov_b32_e32 v42, v127
	v_mov_b32_e32 v41, v127
	v_mov_b32_e32 v40, v127
	v_mov_b32_e32 v39, v127
	v_mov_b32_e32 v38, v127
	v_mov_b32_e32 v37, v127
	v_mov_b32_e32 v36, v127
	v_mov_b32_e32 v35, v127
	v_mov_b32_e32 v34, v127
	v_mov_b32_e32 v33, v127
	v_mov_b32_e32 v32, v127
	v_mov_b32_e32 v31, v127
	v_mov_b32_e32 v30, v127
	v_mov_b32_e32 v29, v127
	v_mov_b32_e32 v28, v127
	v_mov_b32_e32 v27, v127
	v_mov_b32_e32 v26, v127
	v_mov_b32_e32 v25, v127
	v_mov_b32_e32 v24, v127
	v_mov_b32_e32 v23, v127
	v_mov_b32_e32 v22, v127
	v_mov_b32_e32 v21, v127
	v_mov_b32_e32 v20, v127
	v_mov_b32_e32 v19, v127
	v_mov_b32_e32 v18, v127
	v_mov_b32_e32 v17, v127
	v_mov_b32_e32 v16, v127
	v_mov_b32_e32 v15, v127
	v_mov_b32_e32 v14, v127
	v_mov_b32_e32 v13, v127
	v_mov_b32_e32 v12, v127
	v_mov_b32_e32 v11, v127
	v_mov_b32_e32 v10, v127
	v_mov_b32_e32 v9, v127
	v_mov_b32_e32 v8, v127
	v_mov_b32_e32 v7, v127
	v_mov_b32_e32 v6, v127
	v_mov_b32_e32 v5, v127
	v_mov_b32_e32 v4, v127
	v_mov_b32_e32 v3, v127
	v_mov_b32_e32 v2, v127
	v_mov_b32_e32 v1, v127
	v_mov_b32_e32 v0, v127
	s_waitcnt lgkmcnt(0)
	s_barrier
	s_cbranch_scc1 .LBB0_25
	v_mov_b32_e32 v0, 0
	s_mov_b32 s27, 0
	v_mov_b32_e32 v1, v0
	v_mov_b32_e32 v2, v0
	v_mov_b32_e32 v3, v0
	v_mov_b32_e32 v4, v0
	v_mov_b32_e32 v5, v0
	v_mov_b32_e32 v6, v0
	v_mov_b32_e32 v7, v0
	v_mov_b32_e32 v8, v0
	v_mov_b32_e32 v9, v0
	v_mov_b32_e32 v10, v0
	v_mov_b32_e32 v11, v0
	v_mov_b32_e32 v12, v0
	v_mov_b32_e32 v13, v0
	v_mov_b32_e32 v14, v0
	v_mov_b32_e32 v15, v0
	v_mov_b32_e32 v16, v0
	v_mov_b32_e32 v17, v0
	v_mov_b32_e32 v18, v0
	v_mov_b32_e32 v19, v0
	v_mov_b32_e32 v20, v0
	v_mov_b32_e32 v21, v0
	v_mov_b32_e32 v22, v0
	v_mov_b32_e32 v23, v0
	v_mov_b32_e32 v24, v0
	v_mov_b32_e32 v25, v0
	v_mov_b32_e32 v26, v0
	v_mov_b32_e32 v27, v0
	v_mov_b32_e32 v28, v0
	v_mov_b32_e32 v29, v0
	v_mov_b32_e32 v30, v0
	v_mov_b32_e32 v31, v0
	v_mov_b32_e32 v32, v0
	v_mov_b32_e32 v33, v0
	v_mov_b32_e32 v34, v0
	v_mov_b32_e32 v35, v0
	v_mov_b32_e32 v36, v0
	v_mov_b32_e32 v37, v0
	v_mov_b32_e32 v38, v0
	v_mov_b32_e32 v39, v0
	v_mov_b32_e32 v40, v0
	v_mov_b32_e32 v41, v0
	v_mov_b32_e32 v42, v0
	v_mov_b32_e32 v43, v0
	v_mov_b32_e32 v44, v0
	v_mov_b32_e32 v45, v0
	v_mov_b32_e32 v46, v0
	v_mov_b32_e32 v47, v0
	v_mov_b32_e32 v48, v0
	v_mov_b32_e32 v49, v0
	v_mov_b32_e32 v50, v0
	v_mov_b32_e32 v51, v0
	v_mov_b32_e32 v52, v0
	v_mov_b32_e32 v53, v0
	v_mov_b32_e32 v54, v0
	v_mov_b32_e32 v55, v0
	v_mov_b32_e32 v56, v0
	v_mov_b32_e32 v57, v0
	v_mov_b32_e32 v58, v0
	v_mov_b32_e32 v59, v0
	v_mov_b32_e32 v60, v0
	v_mov_b32_e32 v61, v0
	v_mov_b32_e32 v62, v0
	v_mov_b32_e32 v63, v0
	v_mov_b32_e32 v64, v0
	v_mov_b32_e32 v65, v0
	v_mov_b32_e32 v66, v0
	v_mov_b32_e32 v67, v0
	v_mov_b32_e32 v68, v0
	v_mov_b32_e32 v69, v0
	v_mov_b32_e32 v70, v0
	v_mov_b32_e32 v71, v0
	v_mov_b32_e32 v72, v0
	v_mov_b32_e32 v73, v0
	v_mov_b32_e32 v74, v0
	v_mov_b32_e32 v75, v0
	v_mov_b32_e32 v76, v0
	v_mov_b32_e32 v77, v0
	v_mov_b32_e32 v78, v0
	v_mov_b32_e32 v79, v0
	v_mov_b32_e32 v80, v0
	v_mov_b32_e32 v81, v0
	v_mov_b32_e32 v82, v0
	v_mov_b32_e32 v83, v0
	v_mov_b32_e32 v84, v0
	v_mov_b32_e32 v85, v0
	v_mov_b32_e32 v86, v0
	v_mov_b32_e32 v87, v0
	v_mov_b32_e32 v88, v0
	v_mov_b32_e32 v89, v0
	v_mov_b32_e32 v90, v0
	v_mov_b32_e32 v91, v0
	v_mov_b32_e32 v92, v0
	v_mov_b32_e32 v93, v0
	v_mov_b32_e32 v94, v0
	v_mov_b32_e32 v95, v0
	v_mov_b32_e32 v96, v0
	v_mov_b32_e32 v97, v0
	v_mov_b32_e32 v98, v0
	v_mov_b32_e32 v99, v0
	v_mov_b32_e32 v100, v0
	v_mov_b32_e32 v101, v0
	v_mov_b32_e32 v102, v0
	v_mov_b32_e32 v103, v0
	v_mov_b32_e32 v104, v0
	v_mov_b32_e32 v105, v0
	v_mov_b32_e32 v106, v0
	v_mov_b32_e32 v107, v0
	v_mov_b32_e32 v108, v0
	v_mov_b32_e32 v109, v0
	v_mov_b32_e32 v110, v0
	v_mov_b32_e32 v111, v0
	v_mov_b32_e32 v112, v0
	v_mov_b32_e32 v113, v0
	v_mov_b32_e32 v114, v0
	v_mov_b32_e32 v115, v0
	v_mov_b32_e32 v116, v0
	v_mov_b32_e32 v117, v0
	v_mov_b32_e32 v118, v0
	v_mov_b32_e32 v119, v0
	v_mov_b32_e32 v120, v0
	v_mov_b32_e32 v121, v0
	v_mov_b32_e32 v122, v0
	v_mov_b32_e32 v123, v0
	v_mov_b32_e32 v124, v0
	v_mov_b32_e32 v125, v0
	v_mov_b32_e32 v126, v0
	v_mov_b32_e32 v127, v0

; #define SSTOREG(buf_) do { char* b_ = (buf_) + lo; \
;       *(uint4*)(b_) = ra0; *(uint4*)(b_ + 64 * GSTR) = ra1; *(uint4*)(b_ + 128 * GSTR) = ra2; *(uint4*)(b_ + 192 * GSTR) = ra3; \
;       *(uint4*)(b_ + 256 * GSTR) = rw0; *(uint4*)(b_ + 320 * GSTR) = rw1; \
;       if (WM == 2) { *(uint4*)(b_ + 384 * GSTR) = rw2; *(uint4*)(b_ + 448 * GSTR) = rw3; } } while (0)
; #define SSTOREG(buf_) do { char* b_ = (buf_) + lo; \
;       *(uint4*)(b_) = ra0; *(uint4*)(b_ + 64 * GSTR) = ra1; *(uint4*)(b_ + 128 * GSTR) = ra2; *(uint4*)(b_ + 192 * GSTR) = ra3; \
;       *(uint4*)(b_ + 256 * GSTR) = rw0; *(uint4*)(b_ + 320 * GSTR) = rw1; \
;       if (WM == 2) { *(uint4*)(b_ + 384 * GSTR) = rw2; *(uint4*)(b_ + 448 * GSTR) = rw3; } } while (0)
;     ...
;   for (int u = slot; u < nunits; u += nslots) {
;     const bool part = u >= full;
;     const int q = part ? full + (u - full) / NSP : u, ks = part ? (u - full) % NSP : 0;
;     const int mtl = q / ntiles, nt = q - mtl * ntiles, mt = mtl * 8 + xcd;
;     if (skipctx && (mt % PT) == 0) continue;
;     const int kt0 = part ? (ks * nk) / NSP : 0, kt1 = part ? ((ks + 1) * nk) / NSP : nk;
;     const bf16_t* Ag = A + (size_t)mt * 256 * K;
;     const bf16_t* Wg = W + (size_t)nt * BN * K;
;     f32x16 acc[WM][4];
; #pragma unroll
;     for (int mi = 0; mi < WM; ++mi)
; #pragma unroll
;       for (int nb = 0; nb < 4; ++nb)
; #pragma unroll
;         for (int i = 0; i < 16; ++i) acc[mi][nb][i] = 0.f;
;     uint4 ra0, ra1, ra2, ra3, rw0, rw1, rw2, rw3;
;     rw2 = make_uint4(0, 0, 0, 0); rw3 = rw2;
;     const int grow = tid >> 3, gcol = (tid & 7) * 8;
;     const bf16_t* ap = Ag + (size_t)grow * K + gcol;
;     const bf16_t* wp = Wg + (size_t)grow * K + gcol;
;     const int lo = grow * GSTR + (tid & 7) * 16;
;     ...
;     GLOADG(kt0); SSTOREG(smem);
;     if (WM == 2) GLOADG(kt0 + 1 < kt1 ? kt0 + 1 : kt0);
;   DI void operator()(f32x16 (&acc)[4], int tok0, int nt, int lane, bool part = false) const {
;     ...
;     const int b = tok0 / PL, pp0 = tok0 - b * PL;
;     const float* g = gate + (size_t)(pp0 < CTXL ? 4 : b) * 6144;
;     float* xb = pp0 < CTXL ? (float*)(p->ws + OFF_CTXX) + (size_t)(b * CTXL + pp0) * DM : p->out + (size_t)(b * SEQ + pp0 - CTXL) * DM;
.LBB0_99:
	s_cmp_ge_i32 s45, s46
	s_cselect_b64 s[0:1], -1, 0
	s_sub_i32 s24, s45, s46
	s_lshr_b32 s25, s24, 3
	s_add_i32 s25, s25, s46
	s_cmp_lt_i32 s45, s46
	s_cselect_b64 s[30:31], -1, 0
	s_and_b64 s[28:29], s[30:31], exec
	s_cselect_b32 s25, s45, s25
	s_ashr_i32 s27, s25, 31
	s_lshr_b32 s27, s27, 30
	s_add_i32 s27, s25, s27
	s_ashr_i32 s27, s27, 2
	s_lshl_b32 s28, s27, 3
	s_or_b32 s28, s28, s3
	s_mul_hi_i32 s29, s28, 0x3e0f83e1
	s_lshr_b32 s36, s29, 31
	s_ashr_i32 s29, s29, 3
	s_add_i32 s29, s29, s36
	s_mul_i32 s29, s29, 33
	s_sub_i32 s29, s28, s29
	s_cmp_eq_u32 s29, 0
	s_cselect_b64 s[36:37], -1, 0
	s_and_b64 s[36:37], s[40:41], s[36:37]
	s_and_b64 vcc, exec, s[36:37]
	s_cbranch_vccnz .LBB0_98
	s_lshl_b32 s27, s27, 2
	s_and_b32 s24, s24, 7
	s_sub_i32 s38, s25, s27
	s_lshl_b32 s27, s24, 1
	s_lshl_b32 s24, s24, 4
	s_add_i32 s24, s24, 16
	s_lshr_b32 s36, s24, 3
	s_ashr_i32 s29, s28, 31
	s_ashr_i32 s39, s38, 31
	s_and_b64 s[24:25], s[30:31], exec
	s_cselect_b32 s27, 0, s27
	s_cselect_b32 s30, 16, s36
	s_lshl_b64 s[24:25], s[28:29], 19
	v_lshl_add_u64 v[170:171], v[162:163], 0, s[24:25]
	s_lshl_b64 s[24:25], s[38:39], 19
	v_lshl_add_u64 v[172:173], v[164:165], 0, s[24:25]
	s_mov_b64 s[24:25], 0x20000
	s_lshl_b32 s96, s27, 7
	v_lshl_add_u64 v[174:175], v[170:171], 0, s[24:25]
	s_waitcnt vmcnt(6)
	v_lshl_add_u64 v[180:181], v[172:173], 0, s[24:25]
	s_or_b32 s24, s27, 1
	s_mov_b64 s[36:37], 0x40000
	s_mov_b64 s[42:43], 0x60000
	s_cmp_lt_u32 s24, s30
	v_lshl_add_u64 v[176:177], v[170:171], 0, s[36:37]
	s_waitcnt vmcnt(4)
	v_lshl_add_u64 v[178:179], v[170:171], 0, s[42:43]
	v_lshl_add_u64 v[182:183], v[172:173], 0, s[36:37]
	v_lshl_add_u64 v[184:185], v[172:173], 0, s[42:43]
	s_cselect_b32 s24, s24, s27
	v_lshl_add_u64 v[0:1], v[170:171], 0, s[96:97]
	v_lshl_add_u64 v[4:5], v[174:175], 0, s[96:97]
	v_lshl_add_u64 v[8:9], v[176:177], 0, s[96:97]
	v_lshl_add_u64 v[12:13], v[178:179], 0, s[96:97]
	v_lshl_add_u64 v[16:17], v[172:173], 0, s[96:97]
	v_lshl_add_u64 v[20:21], v[180:181], 0, s[96:97]
	v_lshl_add_u64 v[24:25], v[182:183], 0, s[96:97]
	v_lshl_add_u64 v[28:29], v[184:185], 0, s[96:97]
	s_lshl_b32 s96, s24, 7
	v_lshl_add_u64 v[32:33], v[170:171], 0, s[96:97]
	global_load_dwordx4 v[0:3], v[0:1], off
	s_nop 0
	global_load_dwordx4 v[4:7], v[4:5], off
	s_nop 0
	global_load_dwordx4 v[8:11], v[8:9], off
	s_nop 0
	global_load_dwordx4 v[12:15], v[12:13], off
	s_nop 0
	global_load_dwordx4 v[16:19], v[16:17], off
	s_nop 0
	global_load_dwordx4 v[20:23], v[20:21], off
	s_nop 0
	global_load_dwordx4 v[24:27], v[24:25], off
	s_nop 0
	global_load_dwordx4 v[28:31], v[28:29], off
	v_lshl_add_u64 v[34:35], v[174:175], 0, s[96:97]
	v_lshl_add_u64 v[36:37], v[176:177], 0, s[96:97]
	v_lshl_add_u64 v[38:39], v[178:179], 0, s[96:97]
	v_lshl_add_u64 v[40:41], v[172:173], 0, s[96:97]
	v_lshl_add_u64 v[42:43], v[180:181], 0, s[96:97]
	v_lshl_add_u64 v[44:45], v[182:183], 0, s[96:97]
	v_lshl_add_u64 v[46:47], v[184:185], 0, s[96:97]
	global_load_dwordx4 v[158:161], v[32:33], off
	global_load_dwordx4 v[154:157], v[34:35], off
	global_load_dwordx4 v[150:153], v[36:37], off
	global_load_dwordx4 v[146:149], v[38:39], off
	global_load_dwordx4 v[142:145], v[40:41], off
	global_load_dwordx4 v[136:139], v[42:43], off
	global_load_dwordx4 v[132:135], v[44:45], off
	global_load_dwordx4 v[128:131], v[46:47], off
	s_mul_i32 s32, s28, 0x7c2
	s_lshr_b32 s32, s32, 16
	s_mul_i32 s98, s32, 33
	s_sub_u32 s98, s28, s98
	s_cmp_eq_u32 s98, 0
	s_cbranch_scc1 .Lpf2_ctx
	s_lshl_b32 s99, s98, 8
	s_lshl_b32 s32, s32, 13
	s_add_u32 s32, s32, s99
	s_addk_i32 s32, 0xff00
	v_readlane_b32 s98, v254, 59
	v_readlane_b32 s99, v254, 60
	s_branch .Lpf2_join

; #define SSTOREG(buf_) do { char* b_ = (buf_) + lo; \
;       *(uint4*)(b_) = ra0; *(uint4*)(b_ + 64 * GSTR) = ra1; *(uint4*)(b_ + 128 * GSTR) = ra2; *(uint4*)(b_ + 192 * GSTR) = ra3; \
;       *(uint4*)(b_ + 256 * GSTR) = rw0; *(uint4*)(b_ + 320 * GSTR) = rw1; \
;       if (WM == 2) { *(uint4*)(b_ + 384 * GSTR) = rw2; *(uint4*)(b_ + 448 * GSTR) = rw3; } } while (0)
; #define SSTOREG(buf_) do { char* b_ = (buf_) + lo; \
;       *(uint4*)(b_) = ra0; *(uint4*)(b_ + 64 * GSTR) = ra1; *(uint4*)(b_ + 128 * GSTR) = ra2; *(uint4*)(b_ + 192 * GSTR) = ra3; \
;       *(uint4*)(b_ + 256 * GSTR) = rw0; *(uint4*)(b_ + 320 * GSTR) = rw1; \
;       if (WM == 2) { *(uint4*)(b_ + 384 * GSTR) = rw2; *(uint4*)(b_ + 448 * GSTR) = rw3; } } while (0)
;     ...
;     f32x16 acc[WM][4];
; #pragma unroll
;     for (int mi = 0; mi < WM; ++mi)
; #pragma unroll
;       for (int nb = 0; nb < 4; ++nb)
; #pragma unroll
;         for (int i = 0; i < 16; ++i) acc[mi][nb][i] = 0.f;
;     uint4 ra0, ra1, ra2, ra3, rw0, rw1, rw2, rw3;
;     rw2 = make_uint4(0, 0, 0, 0); rw3 = rw2;
;     const int grow = tid >> 3, gcol = (tid & 7) * 8;
;     const bf16_t* ap = Ag + (size_t)grow * K + gcol;
;     const bf16_t* wp = Wg + (size_t)grow * K + gcol;
;     const int lo = grow * GSTR + (tid & 7) * 16;
;     ...
;     GLOADG(kt0); SSTOREG(smem);
;     if (WM == 2) GLOADG(kt0 + 1 < kt1 ? kt0 + 1 : kt0);
;     __syncthreads();
;   DI void operator()(f32x16 (&acc)[4], int tok0, int nt, int lane, bool part = false) const {
;     ...
;     const int b = tok0 / PL, pp0 = tok0 - b * PL;
;     const float* g = gate + (size_t)(pp0 < CTXL ? 4 : b) * 6144;
;     float* xb = pp0 < CTXL ? (float*)(p->ws + OFF_CTXX) + (size_t)(b * CTXL + pp0) * DM : p->out + (size_t)(b * SEQ + pp0 - CTXL) * DM;
;     float gv[4];
; #pragma unroll
;     for (int nb = 0; nb < 4; ++nb) gv[nb] = g[nt * 128 + nb * 32 + l31] * sc;
;     float* xc = xb + nt * 128;
;     const int loff = l31 + hh * 4 * DM;
.Lpf2_join:
	s_lshl_b32 s32, s32, 12
	s_add_u32 s98, s98, s32
	s_addc_u32 s99, s99, 0
	v_lshrrev_b32_e32 v250, 3, v167
	v_and_b32_e32 v251, 7, v167
	v_lshlrev_b32_e32 v250, 12, v250
	v_lshl_or_b32 v250, v251, 7, v250
	v_lshl_add_u32 v250, s38, 10, v250
	global_load_dword v251, v250, s[98:99]
	v_add_u32_e32 v250, 0x40000, v250
	global_load_dword v251, v250, s[98:99]
	v_add_u32_e32 v250, 0x40000, v250
	global_load_dword v251, v250, s[98:99]
	v_add_u32_e32 v250, 0x40000, v250
	global_load_dword v251, v250, s[98:99]
	v_mov_b32_e32 v127, 0
	s_mov_b64 s[16:17], 0x20000
	s_mov_b64 s[18:19], 0x40000
	s_mov_b64 s[10:11], 0x60000
	v_mov_b32_e32 v126, v127
	v_mov_b32_e32 v125, v127
	v_mov_b32_e32 v124, v127
	v_mov_b32_e32 v123, v127
	v_mov_b32_e32 v122, v127
	v_mov_b32_e32 v121, v127
	v_mov_b32_e32 v120, v127
	v_mov_b32_e32 v119, v127
	v_mov_b32_e32 v118, v127
	v_mov_b32_e32 v117, v127
	v_mov_b32_e32 v116, v127
	v_mov_b32_e32 v115, v127
	v_mov_b32_e32 v114, v127
	v_mov_b32_e32 v113, v127
	v_mov_b32_e32 v112, v127
	v_mov_b32_e32 v111, v127
	v_mov_b32_e32 v110, v127
	v_mov_b32_e32 v109, v127
	s_cmp_ge_u32 s27, s30
	v_mov_b32_e32 v108, v127
	v_mov_b32_e32 v107, v127
	v_mov_b32_e32 v106, v127
	s_waitcnt vmcnt(23)
	v_mov_b32_e32 v105, v127
	s_waitcnt vmcnt(22)
	v_mov_b32_e32 v104, v127
	s_waitcnt vmcnt(21)
	v_mov_b32_e32 v103, v127
	s_waitcnt vmcnt(20)
	v_mov_b32_e32 v102, v127
	v_mov_b32_e32 v101, v127
	v_mov_b32_e32 v100, v127
	v_mov_b32_e32 v99, v127
	v_mov_b32_e32 v98, v127
	v_mov_b32_e32 v97, v127
	v_mov_b32_e32 v96, v127
	v_mov_b32_e32 v95, v127
	v_mov_b32_e32 v94, v127
	v_mov_b32_e32 v93, v127
	s_waitcnt vmcnt(19)
	ds_write_b128 v188, v[0:3]
	s_waitcnt vmcnt(15)
	ds_write_b128 v188, v[16:19] offset:36864
	ds_write_b128 v188, v[4:7] offset:9216
	ds_write_b128 v188, v[8:11] offset:18432
	ds_write_b128 v188, v[12:15] offset:27648
	s_waitcnt vmcnt(14)
	ds_write_b128 v188, v[20:23] offset:46080
	s_waitcnt vmcnt(13)
	ds_write_b128 v188, v[24:27] offset:55296
	s_waitcnt vmcnt(12)
	ds_write_b128 v188, v[28:31] offset:64512
	v_mov_b32_e32 v92, v127
	v_mov_b32_e32 v91, v127
	v_mov_b32_e32 v90, v127
	v_mov_b32_e32 v89, v127
	v_mov_b32_e32 v88, v127
	v_mov_b32_e32 v87, v127
	v_mov_b32_e32 v86, v127
	v_mov_b32_e32 v85, v127
	v_mov_b32_e32 v84, v127
	v_mov_b32_e32 v83, v127
	v_mov_b32_e32 v82, v127
	v_mov_b32_e32 v81, v127
	v_mov_b32_e32 v80, v127
	v_mov_b32_e32 v79, v127
	v_mov_b32_e32 v78, v127
	v_mov_b32_e32 v77, v127
	v_mov_b32_e32 v76, v127
	v_mov_b32_e32 v75, v127
	v_mov_b32_e32 v74, v127
	v_mov_b32_e32 v73, v127
	v_mov_b32_e32 v72, v127
	v_mov_b32_e32 v71, v127
	v_mov_b32_e32 v70, v127
	v_mov_b32_e32 v69, v127
	v_mov_b32_e32 v68, v127
	v_mov_b32_e32 v67, v127
	v_mov_b32_e32 v66, v127
	v_mov_b32_e32 v65, v127
	v_mov_b32_e32 v64, v127
	v_mov_b32_e32 v63, v127
	v_mov_b32_e32 v62, v127
	v_mov_b32_e32 v61, v127
	v_mov_b32_e32 v60, v127
	v_mov_b32_e32 v59, v127
	v_mov_b32_e32 v58, v127
	v_mov_b32_e32 v57, v127
	v_mov_b32_e32 v56, v127
	v_mov_b32_e32 v55, v127
	v_mov_b32_e32 v54, v127
	v_mov_b32_e32 v53, v127
	v_mov_b32_e32 v52, v127
	v_mov_b32_e32 v51, v127
	v_mov_b32_e32 v50, v127
	v_mov_b32_e32 v49, v127
	v_mov_b32_e32 v48, v127
	v_mov_b32_e32 v47, v127
	v_mov_b32_e32 v46, v127
	v_mov_b32_e32 v45, v127
	v_mov_b32_e32 v44, v127
	v_mov_b32_e32 v43, v127
	v_mov_b32_e32 v42, v127
	v_mov_b32_e32 v41, v127
	v_mov_b32_e32 v40, v127
	v_mov_b32_e32 v39, v127
	v_mov_b32_e32 v38, v127
	v_mov_b32_e32 v37, v127
	v_mov_b32_e32 v36, v127
	v_mov_b32_e32 v35, v127
	v_mov_b32_e32 v34, v127
	v_mov_b32_e32 v33, v127
	v_mov_b32_e32 v32, v127
	v_mov_b32_e32 v31, v127
	v_mov_b32_e32 v30, v127
	v_mov_b32_e32 v29, v127
	v_mov_b32_e32 v28, v127
	v_mov_b32_e32 v27, v127
	v_mov_b32_e32 v26, v127
	v_mov_b32_e32 v25, v127
	v_mov_b32_e32 v24, v127
	v_mov_b32_e32 v23, v127
	v_mov_b32_e32 v22, v127
	v_mov_b32_e32 v21, v127
	v_mov_b32_e32 v20, v127
	v_mov_b32_e32 v19, v127
	v_mov_b32_e32 v18, v127
	v_mov_b32_e32 v17, v127
	v_mov_b32_e32 v16, v127
	v_mov_b32_e32 v15, v127
	v_mov_b32_e32 v14, v127
	v_mov_b32_e32 v13, v127
	v_mov_b32_e32 v12, v127
	v_mov_b32_e32 v11, v127
	v_mov_b32_e32 v10, v127
	v_mov_b32_e32 v9, v127
	v_mov_b32_e32 v8, v127
	v_mov_b32_e32 v7, v127
	v_mov_b32_e32 v6, v127
	v_mov_b32_e32 v5, v127
	v_mov_b32_e32 v4, v127
	v_mov_b32_e32 v3, v127
	v_mov_b32_e32 v2, v127
	v_mov_b32_e32 v1, v127
	v_mov_b32_e32 v0, v127
	s_waitcnt lgkmcnt(0)
	s_barrier
; #define SSTOREG(buf_) do { char* b_ = (buf_) + lo; \
;       *(uint4*)(b_) = ra0; *(uint4*)(b_ + 64 * GSTR) = ra1; *(uint4*)(b_ + 128 * GSTR) = ra2; *(uint4*)(b_ + 192 * GSTR) = ra3; \
;       *(uint4*)(b_ + 256 * GSTR) = rw0; *(uint4*)(b_ + 320 * GSTR) = rw1; \
;       if (WM == 2) { *(uint4*)(b_ + 384 * GSTR) = rw2; *(uint4*)(b_ + 448 * GSTR) = rw3; } } while (0)
; #define SSTOREG(buf_) do { char* b_ = (buf_) + lo; \
;       *(uint4*)(b_) = ra0; *(uint4*)(b_ + 64 * GSTR) = ra1; *(uint4*)(b_ + 128 * GSTR) = ra2; *(uint4*)(b_ + 192 * GSTR) = ra3; \
;       *(uint4*)(b_ + 256 * GSTR) = rw0; *(uint4*)(b_ + 320 * GSTR) = rw1; \
;       if (WM == 2) { *(uint4*)(b_ + 384 * GSTR) = rw2; *(uint4*)(b_ + 448 * GSTR) = rw3; } } while (0)
;     ...
;     f32x16 acc[WM][4];
; #pragma unroll
;     for (int mi = 0; mi < WM; ++mi)
; #pragma unroll
;       for (int nb = 0; nb < 4; ++nb)
; #pragma unroll
;         for (int i = 0; i < 16; ++i) acc[mi][nb][i] = 0.f;
;     uint4 ra0, ra1, ra2, ra3, rw0, rw1, rw2, rw3;
;     rw2 = make_uint4(0, 0, 0, 0); rw3 = rw2;
;     const int grow = tid >> 3, gcol = (tid & 7) * 8;
;     const bf16_t* ap = Ag + (size_t)grow * K + gcol;
;     const bf16_t* wp = Wg + (size_t)grow * K + gcol;
;     const int lo = grow * GSTR + (tid & 7) * 16;
;     ...
;     GLOADG(kt0); SSTOREG(smem);
;     if (WM == 2) GLOADG(kt0 + 1 < kt1 ? kt0 + 1 : kt0);
;     __syncthreads();
;     for (int kt = kt0; kt < kt1; ++kt) {
	s_cbranch_scc1 .LBB0_103
	v_mov_b32_e32 v0, 0
	v_mov_b32_e32 v1, v0
	v_mov_b32_e32 v2, v0
	v_mov_b32_e32 v3, v0
	v_mov_b32_e32 v4, v0
	v_mov_b32_e32 v5, v0
	v_mov_b32_e32 v6, v0
	v_mov_b32_e32 v7, v0
	v_mov_b32_e32 v8, v0
	v_mov_b32_e32 v9, v0
	v_mov_b32_e32 v10, v0
	v_mov_b32_e32 v11, v0
	v_mov_b32_e32 v12, v0
	v_mov_b32_e32 v13, v0
	v_mov_b32_e32 v14, v0
	v_mov_b32_e32 v15, v0
	v_mov_b32_e32 v16, v0
	v_mov_b32_e32 v17, v0
	v_mov_b32_e32 v18, v0
	v_mov_b32_e32 v19, v0
	v_mov_b32_e32 v20, v0
	v_mov_b32_e32 v21, v0
	v_mov_b32_e32 v22, v0
	v_mov_b32_e32 v23, v0
	v_mov_b32_e32 v24, v0
	v_mov_b32_e32 v25, v0
	v_mov_b32_e32 v26, v0
	v_mov_b32_e32 v27, v0
	v_mov_b32_e32 v28, v0
	v_mov_b32_e32 v29, v0
	v_mov_b32_e32 v30, v0
	v_mov_b32_e32 v31, v0
	v_mov_b32_e32 v32, v0
	v_mov_b32_e32 v33, v0
	v_mov_b32_e32 v34, v0
	v_mov_b32_e32 v35, v0
	v_mov_b32_e32 v36, v0
	v_mov_b32_e32 v37, v0
	v_mov_b32_e32 v38, v0
	v_mov_b32_e32 v39, v0
	v_mov_b32_e32 v40, v0
	v_mov_b32_e32 v41, v0
	v_mov_b32_e32 v42, v0
	v_mov_b32_e32 v43, v0
	v_mov_b32_e32 v44, v0
	v_mov_b32_e32 v45, v0
	v_mov_b32_e32 v46, v0
	v_mov_b32_e32 v47, v0
	v_mov_b32_e32 v48, v0
	v_mov_b32_e32 v49, v0
	v_mov_b32_e32 v50, v0
	v_mov_b32_e32 v51, v0
	v_mov_b32_e32 v52, v0
	v_mov_b32_e32 v53, v0
	v_mov_b32_e32 v54, v0
	v_mov_b32_e32 v55, v0
	v_mov_b32_e32 v56, v0
	v_mov_b32_e32 v57, v0
	v_mov_b32_e32 v58, v0
	v_mov_b32_e32 v59, v0
	v_mov_b32_e32 v60, v0
	v_mov_b32_e32 v61, v0
	v_mov_b32_e32 v62, v0
	v_mov_b32_e32 v63, v0
	v_mov_b32_e32 v64, v0
	v_mov_b32_e32 v65, v0
	v_mov_b32_e32 v66, v0
	v_mov_b32_e32 v67, v0
	v_mov_b32_e32 v68, v0
	v_mov_b32_e32 v69, v0
	v_mov_b32_e32 v70, v0
	v_mov_b32_e32 v71, v0
	v_mov_b32_e32 v72, v0
	v_mov_b32_e32 v73, v0
	v_mov_b32_e32 v74, v0
	v_mov_b32_e32 v75, v0
	v_mov_b32_e32 v76, v0
	v_mov_b32_e32 v77, v0
	v_mov_b32_e32 v78, v0
	v_mov_b32_e32 v79, v0
	v_mov_b32_e32 v80, v0
	v_mov_b32_e32 v81, v0
	v_mov_b32_e32 v82, v0
	v_mov_b32_e32 v83, v0
	v_mov_b32_e32 v84, v0
	v_mov_b32_e32 v85, v0
	v_mov_b32_e32 v86, v0
	v_mov_b32_e32 v87, v0
	v_mov_b32_e32 v88, v0
	v_mov_b32_e32 v89, v0
	v_mov_b32_e32 v90, v0
	v_mov_b32_e32 v91, v0
	v_mov_b32_e32 v92, v0
	v_mov_b32_e32 v93, v0
	v_mov_b32_e32 v94, v0
	v_mov_b32_e32 v95, v0
	v_mov_b32_e32 v96, v0
	v_mov_b32_e32 v97, v0
	v_mov_b32_e32 v98, v0
	v_mov_b32_e32 v99, v0
	v_mov_b32_e32 v100, v0
	v_mov_b32_e32 v101, v0
	v_mov_b32_e32 v102, v0
	v_mov_b32_e32 v103, v0
	v_mov_b32_e32 v104, v0
	v_mov_b32_e32 v105, v0
	v_mov_b32_e32 v106, v0
	v_mov_b32_e32 v107, v0
	v_mov_b32_e32 v108, v0
	v_mov_b32_e32 v109, v0
	v_mov_b32_e32 v110, v0
	v_mov_b32_e32 v111, v0
	v_mov_b32_e32 v112, v0
	v_mov_b32_e32 v113, v0
	v_mov_b32_e32 v114, v0
	v_mov_b32_e32 v115, v0
	v_mov_b32_e32 v116, v0
	v_mov_b32_e32 v117, v0
	v_mov_b32_e32 v118, v0
	v_mov_b32_e32 v119, v0
	v_mov_b32_e32 v120, v0
	v_mov_b32_e32 v121, v0
	v_mov_b32_e32 v122, v0
	v_mov_b32_e32 v123, v0
	v_mov_b32_e32 v124, v0
	v_mov_b32_e32 v125, v0
	v_mov_b32_e32 v126, v0
	v_mov_b32_e32 v127, v0
